# QKV epilogue: dwordx2 stores widened to dwordx4 via v_permlane16_swap pairs; rope-table loads hoisted with counted vmcnt; earlier loop prefetch edits
# speedup vs baseline: 1.0061x; 1.0014x over previous
;     __device__ __forceinline__ void operator()(f32x4 (&acc)[2][2][4][2], const Unit& u, int wr, int wc, int fr, int fq) const {
;     ...
;                 bf16_t* rowp = O + (size_t)row * INC + col0;
; #pragma unroll
;                 for (int bj = 0; bj < 2; ++bj)
; #pragma unroll
;                     for (int n = 0; n < 2; ++n) { const f32x4 v = acc[ai][bj][m][n] * (scale * rt[u.i * 256 + wr * 64 + fr + ai * HALF + m * 16]); u32x2 w; w.x = pk2(v[0], v[1]); w.y = pk2(v[2], v[3]); *(u32x2*)(rowp + bj * HALF + n * 16) = w; }
.LBB0_743:
	ds_read_b32 v20, v154 offset:704
	v_mov_b64_e32 v[18:19], s[72:73]
	v_mad_i64_i32 v[16:17], s[4:5], v16, s43, v[18:19]
	v_lshl_add_u64 v[16:17], v[142:143], 1, v[16:17]
	s_waitcnt lgkmcnt(0)
	v_mul_f32_e32 v18, v145, v20
	v_pk_mul_f32 v[14:15], v[14:15], v[18:19] op_sel_hi:[1,0]
	v_pk_mul_f32 v[12:13], v[12:13], v[18:19] op_sel_hi:[1,0]
	v_pk_mul_f32 v[10:11], v[10:11], v[18:19] op_sel_hi:[1,0]
	v_pk_mul_f32 v[8:9], v[8:9], v[18:19] op_sel_hi:[1,0]
	v_pk_mul_f32 v[6:7], v[6:7], v[18:19] op_sel_hi:[1,0]
	v_pk_mul_f32 v[4:5], v[4:5], v[18:19] op_sel_hi:[1,0]
	v_pk_mul_f32 v[2:3], v[2:3], v[18:19] op_sel_hi:[1,0]
	v_pk_mul_f32 v[0:1], v[0:1], v[18:19] op_sel_hi:[1,0]
	v_cvt_pk_bf16_f32 v12, v12, v13
	v_cvt_pk_bf16_f32 v13, v14, v15
	v_cvt_pk_bf16_f32 v8, v8, v9
	v_cvt_pk_bf16_f32 v9, v10, v11
	v_cvt_pk_bf16_f32 v4, v4, v5
	v_cvt_pk_bf16_f32 v5, v6, v7
	v_cvt_pk_bf16_f32 v0, v0, v1
	v_cvt_pk_bf16_f32 v1, v2, v3
	s_and_b64 vcc, exec, s[0:1]
	s_mov_b32 s46, s45
	s_mov_b32 s47, s12
	s_mov_b32 s4, s10
	s_mov_b64 s[20:21], s[16:17]
	s_mov_b64 s[18:19], s[14:15]
	s_nop 1
	v_permlane16_swap_b32_e32 v12, v8
	v_permlane16_swap_b32_e32 v13, v9
	v_permlane16_swap_b32_e32 v4, v0
	v_permlane16_swap_b32_e32 v5, v1
	v_mov_b32_e32 v14, v8
	v_mov_b32_e32 v15, v9
	v_mov_b32_e32 v6, v0
	v_mov_b32_e32 v7, v1
	v_lshl_add_u64 v[246:247], v[16:17], 0, v[244:245]
	global_store_dwordx4 v[246:247], v[12:15], off
	global_store_dwordx4 v[246:247], v[4:7], off offset:256
	s_nop 1
	s_cbranch_vccnz .LBB0_764

; #define PG8_STAGE(bufoff, gbase, voff) do { _Pragma("unroll") for (int _i = 0; _i < 2; ++_i) \
;         __builtin_amdgcn_global_load_lds((const unsigned*)((const char*)(gbase) + (voff)[_i]), (LAS unsigned*)(lds + (bufoff) + ldsw + _i * 8192), 16, 0, 0); } while (0)
; #define PG8_LDA(dst, b, h) do { _Pragma("unroll") for (int m = 0; m < 4; ++m) _Pragma("unroll") for (int k = 0; k < 2; ++k) dst[m][k] = *(const LAS bf16x8*)(lds + PG8_SA(b, h) + aoff + m * 2048 + k * 1024); } while (0)
; #define PG8_LDB(dst, b, h) do { _Pragma("unroll") for (int n = 0; n < 2; ++n) _Pragma("unroll") for (int k = 0; k < 2; ++k) dst[n][k] = *(const LAS bf16x8*)(lds + PG8_SB(b, h) + boff + n * 2048 + k * 1024); } while (0)
; #define PG8_MMA(ai, bj, At, Bt) do { __builtin_amdgcn_s_setprio(1); _Pragma("unroll") for (int m = 0; m < 4; ++m) _Pragma("unroll") for (int n = 0; n < 2; ++n) _Pragma("unroll") for (int k = 0; k < 2; ++k) \
;         acc[ai][bj][m][n] = __builtin_amdgcn_mfma_f32_16x16x32_bf16(Bt[n][k], At[m][k], acc[ai][bj][m][n], 0, 0, 0); __builtin_amdgcn_s_setprio(0); } while (0)
; #define PG8_WAIT_L(n) asm volatile("s_waitcnt lgkmcnt(" #n ")" ::: "memory")
; #define PG8_BAR __builtin_amdgcn_s_barrier()
; #define PG8_SCHED __builtin_amdgcn_sched_barrier(0)
; template <class Epi>
; __device__ __forceinline__ void gemm_phase(LAS unsigned char* lds, const Gemm g, const Order& S, const Epi& E, const int tid) {
;     ...
;             PG8_LDB(B0, 0, 0); PG8_SCHED; PG8_LDA(At, 0, 0); PG8_STAGE(PG8_SA(1, 1), a1 + hstepA, voffA);
;             PG8_WAIT_L(8); PG8_BAR; PG8_WAIT_L(0); PG8_MMA(0, 0, At, B0); PG8_BAR; PG8_SCHED;
;             PG8_LDB(B1, 0, 1); PG8_STAGE(PG8_SB(0, 0), b2, voffB);
;             PG8_BAR; PG8_WAIT_L(0); PG8_MMA(0, 1, At, B1); PG8_BAR;
;             PG8_LDA(At, 0, 1); PG8_STAGE(PG8_SA(0, 0), a2, voffA);
;             PG8_BAR; PG8_WAIT_L(0); PG8_MMA(1, 0, At, B0); PG8_BAR; PG8_SCHED;
.LBB0_747:
	ds_read_b128 v[142:145], v150
	ds_read_b128 v[154:157], v150 offset:1024
	ds_read_b128 v[158:161], v150 offset:2048
	ds_read_b128 v[162:165], v150 offset:3072
	s_add_u32 s20, s18, 0xfff80080
	s_addc_u32 s21, s19, -1
	s_cmp_eq_u32 s51, 28
	s_cselect_b32 s27, s5, s21
	s_cselect_b32 s26, s11, s20
	s_cselect_b32 s21, s13, s50
	s_cselect_b32 s20, s48, s49
	v_lshl_add_u64 v[198:199], s[18:19], 0, v[134:135]
	s_add_i32 m0, s31, 0xc000
	ds_read_b128 v[166:169], v151
	ds_read_b128 v[170:173], v151 offset:1024
	ds_read_b128 v[174:177], v151 offset:2048
	ds_read_b128 v[178:181], v151 offset:3072
	ds_read_b128 v[182:185], v151 offset:4096
	ds_read_b128 v[186:189], v151 offset:5120
	ds_read_b128 v[190:193], v151 offset:6144
	ds_read_b128 v[194:197], v151 offset:7168
	global_load_lds_dwordx4 v[198:199], off
	v_lshl_add_u64 v[198:199], s[18:19], 0, v[136:137]
	s_add_i32 m0, s31, 0xe000
	s_nop 0
	global_load_lds_dwordx4 v[198:199], off
	s_waitcnt lgkmcnt(8)
	s_barrier
	s_waitcnt lgkmcnt(0)
	s_setprio 1
	s_waitcnt lgkmcnt(0)
	v_mfma_f32_16x16x32_bf16 v[124:127], v[142:145], v[166:169], v[124:127]
	v_mfma_f32_16x16x32_bf16 v[120:123], v[158:161], v[166:169], v[120:123]
	v_mfma_f32_16x16x32_bf16 v[108:111], v[142:145], v[174:177], v[108:111]
	v_mfma_f32_16x16x32_bf16 v[104:107], v[158:161], v[174:177], v[104:107]
	v_mfma_f32_16x16x32_bf16 v[92:95], v[142:145], v[182:185], v[92:95]
	v_mfma_f32_16x16x32_bf16 v[88:91], v[158:161], v[182:185], v[88:91]
	v_mfma_f32_16x16x32_bf16 v[76:79], v[142:145], v[190:193], v[76:79]
	v_mfma_f32_16x16x32_bf16 v[72:75], v[158:161], v[190:193], v[72:75]
	v_mfma_f32_16x16x32_bf16 v[124:127], v[154:157], v[170:173], v[124:127]
	v_mfma_f32_16x16x32_bf16 v[120:123], v[162:165], v[170:173], v[120:123]
	v_mfma_f32_16x16x32_bf16 v[108:111], v[154:157], v[178:181], v[108:111]
	v_mfma_f32_16x16x32_bf16 v[104:107], v[162:165], v[178:181], v[104:107]
	v_mfma_f32_16x16x32_bf16 v[92:95], v[154:157], v[186:189], v[92:95]
	v_mfma_f32_16x16x32_bf16 v[88:91], v[162:165], v[186:189], v[88:91]
	v_mfma_f32_16x16x32_bf16 v[76:79], v[154:157], v[194:197], v[76:79]
	v_mfma_f32_16x16x32_bf16 v[72:75], v[162:165], v[194:197], v[72:75]
	s_setprio 0
	s_barrier
	s_add_i32 s52, s41, s29
	v_lshl_add_u64 v[214:215], s[20:21], 0, v[130:131]
	s_mov_b32 m0, s52
	ds_read_b128 v[198:201], v152
	ds_read_b128 v[202:205], v152 offset:1024
	ds_read_b128 v[206:209], v152 offset:2048
	ds_read_b128 v[210:213], v152 offset:3072
	global_load_lds_dwordx4 v[214:215], off
	v_lshl_add_u64 v[216:217], s[20:21], 0, v[128:129]
	s_add_i32 m0, s52, 0x2000
	s_nop 0
	global_load_lds_dwordx4 v[216:217], off
	s_barrier
	s_waitcnt lgkmcnt(0)
	s_setprio 1
	s_waitcnt lgkmcnt(0)
	v_mfma_f32_16x16x32_bf16 v[116:119], v[198:201], v[166:169], v[116:119]
	v_mfma_f32_16x16x32_bf16 v[112:115], v[206:209], v[166:169], v[112:115]
	v_mfma_f32_16x16x32_bf16 v[100:103], v[198:201], v[174:177], v[100:103]
	v_mfma_f32_16x16x32_bf16 v[96:99], v[206:209], v[174:177], v[96:99]
	v_mfma_f32_16x16x32_bf16 v[84:87], v[198:201], v[182:185], v[84:87]
	v_mfma_f32_16x16x32_bf16 v[80:83], v[206:209], v[182:185], v[80:83]
	v_mfma_f32_16x16x32_bf16 v[68:71], v[198:201], v[190:193], v[68:71]
	v_mfma_f32_16x16x32_bf16 v[64:67], v[206:209], v[190:193], v[64:67]
	v_mfma_f32_16x16x32_bf16 v[116:119], v[202:205], v[170:173], v[116:119]
	v_mfma_f32_16x16x32_bf16 v[112:115], v[210:213], v[170:173], v[112:115]
	v_mfma_f32_16x16x32_bf16 v[100:103], v[202:205], v[178:181], v[100:103]
	v_mfma_f32_16x16x32_bf16 v[96:99], v[210:213], v[178:181], v[96:99]
	v_mfma_f32_16x16x32_bf16 v[84:87], v[202:205], v[186:189], v[84:87]
	v_mfma_f32_16x16x32_bf16 v[80:83], v[210:213], v[186:189], v[80:83]
	v_mfma_f32_16x16x32_bf16 v[68:71], v[202:205], v[194:197], v[68:71]
	v_mfma_f32_16x16x32_bf16 v[64:67], v[210:213], v[194:197], v[64:67]
	s_setprio 0
	s_mov_b32 m0, s31
	v_lshl_add_u64 v[218:219], s[26:27], 0, v[130:131]
	s_barrier
	ds_read_b128 v[166:169], v151 offset:16384
	ds_read_b128 v[170:173], v151 offset:17408
	ds_read_b128 v[174:177], v151 offset:18432
	ds_read_b128 v[178:181], v151 offset:19456
	ds_read_b128 v[182:185], v151 offset:20480
	ds_read_b128 v[186:189], v151 offset:21504
	ds_read_b128 v[190:193], v151 offset:22528
	ds_read_b128 v[194:197], v151 offset:23552
	global_load_lds_dwordx4 v[218:219], off
	v_lshl_add_u64 v[220:221], s[26:27], 0, v[128:129]
	s_mov_b32 m0, s33
	s_nop 0
	global_load_lds_dwordx4 v[220:221], off
	s_barrier
	s_waitcnt lgkmcnt(0)
	s_setprio 1
	s_waitcnt lgkmcnt(0)
	v_mfma_f32_16x16x32_bf16 v[60:63], v[142:145], v[166:169], v[60:63]
	v_mfma_f32_16x16x32_bf16 v[56:59], v[158:161], v[166:169], v[56:59]
	v_mfma_f32_16x16x32_bf16 v[44:47], v[142:145], v[174:177], v[44:47]
	v_mfma_f32_16x16x32_bf16 v[40:43], v[158:161], v[174:177], v[40:43]
	v_mfma_f32_16x16x32_bf16 v[28:31], v[142:145], v[182:185], v[28:31]
	v_mfma_f32_16x16x32_bf16 v[24:27], v[158:161], v[182:185], v[24:27]
	v_mfma_f32_16x16x32_bf16 v[12:15], v[142:145], v[190:193], v[12:15]
	v_mfma_f32_16x16x32_bf16 v[8:11], v[158:161], v[190:193], v[8:11]
	v_mfma_f32_16x16x32_bf16 v[60:63], v[154:157], v[170:173], v[60:63]
	v_mfma_f32_16x16x32_bf16 v[56:59], v[162:165], v[170:173], v[56:59]
	v_mfma_f32_16x16x32_bf16 v[44:47], v[154:157], v[178:181], v[44:47]
	v_mfma_f32_16x16x32_bf16 v[40:43], v[162:165], v[178:181], v[40:43]
	v_mfma_f32_16x16x32_bf16 v[28:31], v[154:157], v[186:189], v[28:31]
	v_mfma_f32_16x16x32_bf16 v[24:27], v[162:165], v[186:189], v[24:27]
	v_mfma_f32_16x16x32_bf16 v[12:15], v[154:157], v[194:197], v[12:15]
	v_mfma_f32_16x16x32_bf16 v[8:11], v[162:165], v[194:197], v[8:11]
	s_setprio 0
	s_barrier
; #define PG8_STAGE(bufoff, gbase, voff) do { _Pragma("unroll") for (int _i = 0; _i < 2; ++_i) \
;         __builtin_amdgcn_global_load_lds((const unsigned*)((const char*)(gbase) + (voff)[_i]), (LAS unsigned*)(lds + (bufoff) + ldsw + _i * 8192), 16, 0, 0); } while (0)
; #define PG8_LDA(dst, b, h) do { _Pragma("unroll") for (int m = 0; m < 4; ++m) _Pragma("unroll") for (int k = 0; k < 2; ++k) dst[m][k] = *(const LAS bf16x8*)(lds + PG8_SA(b, h) + aoff + m * 2048 + k * 1024); } while (0)
; #define PG8_LDB(dst, b, h) do { _Pragma("unroll") for (int n = 0; n < 2; ++n) _Pragma("unroll") for (int k = 0; k < 2; ++k) dst[n][k] = *(const LAS bf16x8*)(lds + PG8_SB(b, h) + boff + n * 2048 + k * 1024); } while (0)
; #define PG8_MMA(ai, bj, At, Bt) do { __builtin_amdgcn_s_setprio(1); _Pragma("unroll") for (int m = 0; m < 4; ++m) _Pragma("unroll") for (int n = 0; n < 2; ++n) _Pragma("unroll") for (int k = 0; k < 2; ++k) \
;         acc[ai][bj][m][n] = __builtin_amdgcn_mfma_f32_16x16x32_bf16(Bt[n][k], At[m][k], acc[ai][bj][m][n], 0, 0, 0); __builtin_amdgcn_s_setprio(0); } while (0)
; #define PG8_WAIT_V(n) asm volatile("s_waitcnt vmcnt(" #n ")" ::: "memory")
; #define PG8_WAIT_L(n) asm volatile("s_waitcnt lgkmcnt(" #n ")" ::: "memory")
; #define PG8_BAR __builtin_amdgcn_s_barrier()
; #define PG8_SCHED __builtin_amdgcn_sched_barrier(0)
; template <class Epi>
; __device__ __forceinline__ void gemm_phase(LAS unsigned char* lds, const Gemm g, const Order& S, const Epi& E, const int tid) {
;     ...
;             PG8_STAGE(PG8_SB(0, 1), b2 + hstepB, voffB);
;             PG8_WAIT_V(6); PG8_BAR; PG8_MMA(1, 1, At, B1); PG8_BAR;
;             PG8_LDB(B0, 1, 0); PG8_SCHED; PG8_LDA(At, 1, 0); PG8_STAGE(PG8_SA(0, 1), a2 + hstepA, voffA);
;             PG8_WAIT_L(8); PG8_BAR; PG8_WAIT_L(0); PG8_MMA(0, 0, At, B0); PG8_BAR; PG8_SCHED;
;             PG8_LDB(B1, 1, 1); PG8_STAGE(PG8_SB(1, 0), b3, voffB);
;             PG8_BAR; PG8_WAIT_L(0); PG8_MMA(0, 1, At, B1); PG8_BAR;
;             PG8_LDA(At, 1, 1); PG8_STAGE(PG8_SA(1, 0), a3, voffA);
	s_add_u32 s52, s20, 0x80000
	s_addc_u32 s53, s21, 0
	s_add_i32 s55, s42, s29
	v_lshl_add_u64 v[142:143], s[52:53], 0, v[130:131]
	s_mov_b32 m0, s55
	s_nop 0
	global_load_lds_dwordx4 v[142:143], off
	v_lshl_add_u64 v[142:143], s[52:53], 0, v[128:129]
	s_add_i32 m0, s55, 0x2000
	s_nop 0
	global_load_lds_dwordx4 v[142:143], off
	s_waitcnt vmcnt(6)
	s_barrier
	s_setprio 1
	v_mfma_f32_16x16x32_bf16 v[52:55], v[198:201], v[166:169], v[52:55]
	v_mfma_f32_16x16x32_bf16 v[48:51], v[206:209], v[166:169], v[48:51]
	v_mfma_f32_16x16x32_bf16 v[36:39], v[198:201], v[174:177], v[36:39]
	v_mfma_f32_16x16x32_bf16 v[32:35], v[206:209], v[174:177], v[32:35]
	v_mfma_f32_16x16x32_bf16 v[20:23], v[198:201], v[182:185], v[20:23]
	v_mfma_f32_16x16x32_bf16 v[16:19], v[206:209], v[182:185], v[16:19]
	v_mfma_f32_16x16x32_bf16 v[4:7], v[198:201], v[190:193], v[4:7]
	v_mfma_f32_16x16x32_bf16 v[0:3], v[206:209], v[190:193], v[0:3]
	v_mfma_f32_16x16x32_bf16 v[52:55], v[202:205], v[170:173], v[52:55]
	v_mfma_f32_16x16x32_bf16 v[48:51], v[210:213], v[170:173], v[48:51]
	v_mfma_f32_16x16x32_bf16 v[36:39], v[202:205], v[178:181], v[36:39]
	v_mfma_f32_16x16x32_bf16 v[32:35], v[210:213], v[178:181], v[32:35]
	v_mfma_f32_16x16x32_bf16 v[20:23], v[202:205], v[186:189], v[20:23]
	v_mfma_f32_16x16x32_bf16 v[16:19], v[210:213], v[186:189], v[16:19]
	v_mfma_f32_16x16x32_bf16 v[4:7], v[202:205], v[194:197], v[4:7]
	v_mfma_f32_16x16x32_bf16 v[0:3], v[210:213], v[194:197], v[0:3]
	s_setprio 0
	s_add_i32 s52, 0, 0x18000
	v_add_u32_e32 v162, s52, v147
	s_barrier
	ds_read_b128 v[142:145], v162
	ds_read_b128 v[154:157], v162 offset:1024
	ds_read_b128 v[158:161], v162 offset:2048
	ds_read_b128 v[162:165], v162 offset:3072
	s_add_u32 s26, s26, 0x80000
	s_addc_u32 s27, s27, 0
	s_mov_b32 m0, s34
	v_lshl_add_u64 v[198:199], s[26:27], 0, v[130:131]
	ds_read_b128 v[166:169], v151 offset:32768
	ds_read_b128 v[170:173], v151 offset:33792
	ds_read_b128 v[174:177], v151 offset:34816
	ds_read_b128 v[178:181], v151 offset:35840
	ds_read_b128 v[182:185], v151 offset:36864
	ds_read_b128 v[186:189], v151 offset:37888
	ds_read_b128 v[190:193], v151 offset:38912
	ds_read_b128 v[194:197], v151 offset:39936
	global_load_lds_dwordx4 v[198:199], off
	v_lshl_add_u64 v[198:199], s[26:27], 0, v[128:129]
	s_mov_b32 m0, s35
	s_nop 0
	global_load_lds_dwordx4 v[198:199], off
	s_waitcnt lgkmcnt(8)
	s_barrier
	s_waitcnt lgkmcnt(0)
	s_setprio 1
	s_waitcnt lgkmcnt(0)
	v_mfma_f32_16x16x32_bf16 v[124:127], v[142:145], v[166:169], v[124:127]
	v_mfma_f32_16x16x32_bf16 v[120:123], v[158:161], v[166:169], v[120:123]
	v_mfma_f32_16x16x32_bf16 v[108:111], v[142:145], v[174:177], v[108:111]
	v_mfma_f32_16x16x32_bf16 v[104:107], v[158:161], v[174:177], v[104:107]
	v_mfma_f32_16x16x32_bf16 v[92:95], v[142:145], v[182:185], v[92:95]
	v_mfma_f32_16x16x32_bf16 v[88:91], v[158:161], v[182:185], v[88:91]
	v_mfma_f32_16x16x32_bf16 v[76:79], v[142:145], v[190:193], v[76:79]
	v_mfma_f32_16x16x32_bf16 v[72:75], v[158:161], v[190:193], v[72:75]
	v_mfma_f32_16x16x32_bf16 v[124:127], v[154:157], v[170:173], v[124:127]
	v_mfma_f32_16x16x32_bf16 v[120:123], v[162:165], v[170:173], v[120:123]
	v_mfma_f32_16x16x32_bf16 v[108:111], v[154:157], v[178:181], v[108:111]
	v_mfma_f32_16x16x32_bf16 v[104:107], v[162:165], v[178:181], v[104:107]
	v_mfma_f32_16x16x32_bf16 v[92:95], v[154:157], v[186:189], v[92:95]
	v_mfma_f32_16x16x32_bf16 v[88:91], v[162:165], v[186:189], v[88:91]
	v_mfma_f32_16x16x32_bf16 v[76:79], v[154:157], v[194:197], v[76:79]
	v_mfma_f32_16x16x32_bf16 v[72:75], v[162:165], v[194:197], v[72:75]
	s_setprio 0
	s_barrier
	s_add_i32 s26, 0, 0x1c000
	s_add_i32 s27, s52, s29
	v_add_u32_e32 v210, s26, v147
	v_lshl_add_u64 v[214:215], v[214:215], 0, s[6:7]
	s_mov_b32 m0, s27
	ds_read_b128 v[198:201], v210
	ds_read_b128 v[202:205], v210 offset:1024
	ds_read_b128 v[206:209], v210 offset:2048
	ds_read_b128 v[210:213], v210 offset:3072
	global_load_lds_dwordx4 v[214:215], off
	v_lshl_add_u64 v[214:215], v[216:217], 0, s[6:7]
	s_add_i32 m0, s27, 0x2000
	s_nop 0
	global_load_lds_dwordx4 v[214:215], off
	s_barrier
	s_waitcnt lgkmcnt(0)
	s_setprio 1
	s_waitcnt lgkmcnt(0)
	v_mfma_f32_16x16x32_bf16 v[116:119], v[198:201], v[166:169], v[116:119]
	v_mfma_f32_16x16x32_bf16 v[112:115], v[206:209], v[166:169], v[112:115]
	v_mfma_f32_16x16x32_bf16 v[100:103], v[198:201], v[174:177], v[100:103]
	v_mfma_f32_16x16x32_bf16 v[96:99], v[206:209], v[174:177], v[96:99]
	v_mfma_f32_16x16x32_bf16 v[84:87], v[198:201], v[182:185], v[84:87]
	v_mfma_f32_16x16x32_bf16 v[80:83], v[206:209], v[182:185], v[80:83]
	v_mfma_f32_16x16x32_bf16 v[68:71], v[198:201], v[190:193], v[68:71]
	v_mfma_f32_16x16x32_bf16 v[64:67], v[206:209], v[190:193], v[64:67]
	v_mfma_f32_16x16x32_bf16 v[116:119], v[202:205], v[170:173], v[116:119]
	v_mfma_f32_16x16x32_bf16 v[112:115], v[210:213], v[170:173], v[112:115]
	v_mfma_f32_16x16x32_bf16 v[100:103], v[202:205], v[178:181], v[100:103]
	v_mfma_f32_16x16x32_bf16 v[96:99], v[210:213], v[178:181], v[96:99]
	v_mfma_f32_16x16x32_bf16 v[84:87], v[202:205], v[186:189], v[84:87]
	v_mfma_f32_16x16x32_bf16 v[80:83], v[210:213], v[186:189], v[80:83]
	v_mfma_f32_16x16x32_bf16 v[68:71], v[202:205], v[194:197], v[68:71]
	v_mfma_f32_16x16x32_bf16 v[64:67], v[210:213], v[194:197], v[64:67]
	s_setprio 0
	s_mov_b32 m0, s39
	v_lshl_add_u64 v[214:215], v[218:219], 0, s[6:7]
	s_barrier
	ds_read_b128 v[166:169], v151 offset:49152
	ds_read_b128 v[170:173], v151 offset:50176
	ds_read_b128 v[174:177], v151 offset:51200
	ds_read_b128 v[178:181], v151 offset:52224
	ds_read_b128 v[182:185], v151 offset:53248
	ds_read_b128 v[186:189], v151 offset:54272
	ds_read_b128 v[190:193], v151 offset:55296
	ds_read_b128 v[194:197], v151 offset:56320
	global_load_lds_dwordx4 v[214:215], off
	v_lshl_add_u64 v[214:215], v[220:221], 0, s[6:7]
	s_mov_b32 m0, s40
	s_nop 0
	global_load_lds_dwordx4 v[214:215], off
	s_barrier
; #define PG8_STAGE(bufoff, gbase, voff) do { _Pragma("unroll") for (int _i = 0; _i < 2; ++_i) \
;         __builtin_amdgcn_global_load_lds((const unsigned*)((const char*)(gbase) + (voff)[_i]), (LAS unsigned*)(lds + (bufoff) + ldsw + _i * 8192), 16, 0, 0); } while (0)
; #define PG8_MMA(ai, bj, At, Bt) do { __builtin_amdgcn_s_setprio(1); _Pragma("unroll") for (int m = 0; m < 4; ++m) _Pragma("unroll") for (int n = 0; n < 2; ++n) _Pragma("unroll") for (int k = 0; k < 2; ++k) \
;         acc[ai][bj][m][n] = __builtin_amdgcn_mfma_f32_16x16x32_bf16(Bt[n][k], At[m][k], acc[ai][bj][m][n], 0, 0, 0); __builtin_amdgcn_s_setprio(0); } while (0)
; #define PG8_WAIT_V(n) asm volatile("s_waitcnt vmcnt(" #n ")" ::: "memory")
; #define PG8_WAIT_L(n) asm volatile("s_waitcnt lgkmcnt(" #n ")" ::: "memory")
; #define PG8_BAR __builtin_amdgcn_s_barrier()
; template <class Epi>
; __device__ __forceinline__ void gemm_phase(LAS unsigned char* lds, const Gemm g, const Order& S, const Epi& E, const int tid) {
;     ...
;             PG8_BAR; PG8_WAIT_L(0); PG8_MMA(1, 0, At, B0); PG8_BAR; PG8_SCHED;
;             PG8_STAGE(PG8_SB(1, 1), b3 + hstepB, voffB);
;             PG8_WAIT_V(6); PG8_BAR; PG8_MMA(1, 1, At, B1); PG8_BAR;
;     __device__ __forceinline__ void operator()(f32x4 (&acc)[2][2][4][2], const Unit& u, int wr, int wc, int fr, int fq) const {
;         const int row0 = u.pm * BM + wr * 64 + fr, col0 = u.pn * BM + wc * 32 + 4 * fq;
;         const int sec = u.pn >> 3;
;         const float scale = (sec == 0) ? 0.08838834764831845f : 1.0f;
; #pragma unroll
;         for (int ai = 0; ai < 2; ++ai)
; #pragma unroll
;             for (int m = 0; m < 4; ++m) {
;                 const int row = row0 + ai * HALF + m * 16;
;                 if (sec < 2 && wc == 0) {
;                     const f32x4 t0 = *(const f32x4*)(tab + (size_t)row * 32 + 8 * fq), t1 = *(const f32x4*)(tab + (size_t)row * 32 + 8 * fq + 4);
;                     const float cs[4] = {t0[0], t0[2], t1[0], t1[2]}, sn[4] = {t0[1], t0[3], t1[1], t1[3]};
; #pragma unroll
;                     for (int bj = 0; bj < 2; ++bj)
; #pragma unroll
;                         for (int j = 0; j < 4; ++j) { const float a = acc[ai][bj][m][0][j], b = acc[ai][bj][m][1][j];
;                             acc[ai][bj][m][0][j] = a * cs[j] - b * sn[j]; acc[ai][bj][m][1][j] = b * cs[j] + a * sn[j]; }
	s_waitcnt lgkmcnt(0)
	s_setprio 1
	s_waitcnt lgkmcnt(0)
	v_mfma_f32_16x16x32_bf16 v[60:63], v[142:145], v[166:169], v[60:63]
	v_mfma_f32_16x16x32_bf16 v[56:59], v[158:161], v[166:169], v[56:59]
	v_mfma_f32_16x16x32_bf16 v[44:47], v[142:145], v[174:177], v[44:47]
	v_mfma_f32_16x16x32_bf16 v[40:43], v[158:161], v[174:177], v[40:43]
	v_mfma_f32_16x16x32_bf16 v[28:31], v[142:145], v[182:185], v[28:31]
	v_mfma_f32_16x16x32_bf16 v[24:27], v[158:161], v[182:185], v[24:27]
	v_mfma_f32_16x16x32_bf16 v[12:15], v[142:145], v[190:193], v[12:15]
	v_mfma_f32_16x16x32_bf16 v[8:11], v[158:161], v[190:193], v[8:11]
	v_mfma_f32_16x16x32_bf16 v[60:63], v[154:157], v[170:173], v[60:63]
	v_mfma_f32_16x16x32_bf16 v[56:59], v[162:165], v[170:173], v[56:59]
	v_mfma_f32_16x16x32_bf16 v[44:47], v[154:157], v[178:181], v[44:47]
	v_mfma_f32_16x16x32_bf16 v[40:43], v[162:165], v[178:181], v[40:43]
	v_mfma_f32_16x16x32_bf16 v[28:31], v[154:157], v[186:189], v[28:31]
	v_mfma_f32_16x16x32_bf16 v[24:27], v[162:165], v[186:189], v[24:27]
	v_mfma_f32_16x16x32_bf16 v[12:15], v[154:157], v[194:197], v[12:15]
	v_mfma_f32_16x16x32_bf16 v[8:11], v[162:165], v[194:197], v[8:11]
	s_setprio 0
	s_barrier
	s_add_u32 s20, s20, 0x80080
	s_addc_u32 s21, s21, 0
	s_add_i32 s26, s26, s29
	v_lshl_add_u64 v[142:143], s[20:21], 0, v[130:131]
	s_mov_b32 m0, s26
	s_nop 0
	global_load_lds_dwordx4 v[142:143], off
	v_lshl_add_u64 v[142:143], s[20:21], 0, v[128:129]
	s_add_i32 m0, s26, 0x2000
	s_nop 0
	global_load_lds_dwordx4 v[142:143], off
	s_waitcnt vmcnt(6)
	s_barrier
	s_setprio 1
	v_mfma_f32_16x16x32_bf16 v[52:55], v[198:201], v[166:169], v[52:55]
	v_mfma_f32_16x16x32_bf16 v[48:51], v[206:209], v[166:169], v[48:51]
	v_mfma_f32_16x16x32_bf16 v[36:39], v[198:201], v[174:177], v[36:39]
	v_mfma_f32_16x16x32_bf16 v[32:35], v[206:209], v[174:177], v[32:35]
	v_mfma_f32_16x16x32_bf16 v[20:23], v[198:201], v[182:185], v[20:23]
	v_mfma_f32_16x16x32_bf16 v[16:19], v[206:209], v[182:185], v[16:19]
	v_mfma_f32_16x16x32_bf16 v[4:7], v[198:201], v[190:193], v[4:7]
	v_mfma_f32_16x16x32_bf16 v[0:3], v[206:209], v[190:193], v[0:3]
	v_mfma_f32_16x16x32_bf16 v[52:55], v[202:205], v[170:173], v[52:55]
	v_mfma_f32_16x16x32_bf16 v[48:51], v[210:213], v[170:173], v[48:51]
	v_mfma_f32_16x16x32_bf16 v[36:39], v[202:205], v[178:181], v[36:39]
	v_mfma_f32_16x16x32_bf16 v[32:35], v[210:213], v[178:181], v[32:35]
	v_mfma_f32_16x16x32_bf16 v[20:23], v[202:205], v[186:189], v[20:23]
	v_mfma_f32_16x16x32_bf16 v[16:19], v[210:213], v[186:189], v[16:19]
	v_mfma_f32_16x16x32_bf16 v[4:7], v[202:205], v[194:197], v[4:7]
	v_mfma_f32_16x16x32_bf16 v[0:3], v[210:213], v[194:197], v[0:3]
	s_setprio 0
	s_add_i32 s51, s51, 2
	s_add_u32 s18, s18, 0x100
	s_addc_u32 s19, s19, 0
	s_add_u32 s49, s49, 0x100
	s_addc_u32 s50, s50, 0
	s_cmp_gt_u32 s51, 29
	s_barrier
	s_cbranch_scc0 .LBB0_747
	v_mbcnt_lo_u32_b32 v244, -1, 0
	v_mbcnt_hi_u32_b32 v244, -1, v244
	v_and_b32_e32 v244, 16, v244
	v_lshrrev_b32_e32 v245, 1, v244
	v_add_u32_e32 v244, v244, v245
	v_mov_b32_e32 v245, 0
	s_cmp_lt_i32 s47, 16
	v_lshl_add_u32 v144, s4, 8, v146
	s_cselect_b64 s[4:5], -1, 0
	s_and_b64 s[18:19], s[8:9], s[4:5]
	v_cndmask_b32_e64 v142, 0, 1, s[18:19]
	v_cmp_ne_u32_e64 s[4:5], 1, v142
	s_andn2_b64 vcc, exec, s[18:19]
	v_ashrrev_i32_e32 v145, 31, v144
	s_cbranch_vccnz .LBB0_750
	v_lshlrev_b64 v[142:143], 7, v[144:145]
	v_lshl_add_u64 v[142:143], v[132:133], 0, v[142:143]
	global_load_dwordx4 v[178:181], v[142:143], off
	global_load_dwordx4 v[182:185], v[142:143], off offset:16
	global_load_dwordx4 v[186:189], v[142:143], off offset:2048
	global_load_dwordx4 v[190:193], v[142:143], off offset:2064
	s_movk_i32 s100, 0x1000
	s_mov_b32 s101, 0
	v_lshl_add_u64 v[242:243], v[142:143], 0, s[100:101]
	global_load_dwordx4 v[194:197], v[242:243], off
	global_load_dwordx4 v[198:201], v[242:243], off offset:16
	global_load_dwordx4 v[202:205], v[242:243], off offset:2048
	global_load_dwordx4 v[206:209], v[242:243], off offset:2064
	s_movk_i32 s100, 0x3000
	v_lshl_add_u64 v[242:243], v[242:243], 0, s[100:101]
	global_load_dwordx4 v[210:213], v[242:243], off
	global_load_dwordx4 v[214:217], v[242:243], off offset:16
	global_load_dwordx4 v[218:221], v[242:243], off offset:2048
	global_load_dwordx4 v[222:225], v[242:243], off offset:2064
	s_movk_i32 s100, 0x1000
	v_lshl_add_u64 v[242:243], v[242:243], 0, s[100:101]
	global_load_dwordx4 v[226:229], v[242:243], off
	global_load_dwordx4 v[230:233], v[242:243], off offset:16
	global_load_dwordx4 v[234:237], v[242:243], off offset:2048
	global_load_dwordx4 v[238:241], v[242:243], off offset:2064
	s_waitcnt vmcnt(14)
	v_mov_b32_e32 v154, v178
	v_mov_b32_e32 v155, v179
	v_mov_b32_e32 v156, v180
	v_mov_b32_e32 v157, v181
	v_mov_b32_e32 v158, v182
	v_mov_b32_e32 v159, v183
	v_mov_b32_e32 v160, v184
	v_mov_b32_e32 v161, v185
	v_mov_b32_e32 v142, v154
	v_mov_b32_e32 v143, v156
	v_mov_b32_e32 v156, v155
	v_mul_f32_e32 v154, v126, v158
	v_mul_f32_e32 v162, v122, v159
	v_mul_f32_e32 v164, v122, v158
	v_mul_f32_e32 v166, v126, v159
	v_mov_b32_e32 v122, v127
	v_mov_b32_e32 v126, v123
	v_mul_f32_e32 v168, v118, v158
	v_mul_f32_e32 v170, v114, v159
	v_mul_f32_e32 v158, v114, v158
	v_mul_f32_e32 v172, v118, v159
	v_mov_b32_e32 v114, v119
	v_mov_b32_e32 v118, v115
	v_pk_mul_f32 v[174:175], v[120:121], v[156:157]
	v_pk_mul_f32 v[120:121], v[120:121], v[142:143]
	v_pk_mul_f32 v[122:123], v[122:123], v[160:161]
	v_pk_mul_f32 v[126:127], v[126:127], v[160:161]
	v_pk_mul_f32 v[176:177], v[112:113], v[156:157]
	v_pk_mul_f32 v[114:115], v[114:115], v[160:161]
	v_pk_mul_f32 v[118:119], v[118:119], v[160:161]
	v_pk_mul_f32 v[112:113], v[112:113], v[142:143]
	v_mov_b32_e32 v155, v122
	v_mov_b32_e32 v163, v123
	v_pk_fma_f32 v[160:161], v[124:125], v[142:143], v[174:175] neg_lo:[0,0,1] neg_hi:[0,0,1]
	v_mov_b32_e32 v167, v127
	v_mov_b32_e32 v165, v126
	v_pk_fma_f32 v[120:121], v[124:125], v[156:157], v[120:121]
	v_mov_b32_e32 v169, v114
	v_mov_b32_e32 v171, v115
	v_pk_fma_f32 v[124:125], v[116:117], v[142:143], v[176:177] neg_lo:[0,0,1] neg_hi:[0,0,1]
	v_mov_b32_e32 v173, v119
	v_mov_b32_e32 v159, v118
	v_pk_fma_f32 v[112:113], v[116:117], v[156:157], v[112:113]
	v_pk_add_f32 v[126:127], v[154:155], v[162:163] neg_lo:[0,1] neg_hi:[0,1]
	v_pk_add_f32 v[122:123], v[166:167], v[164:165]
	v_pk_add_f32 v[118:119], v[168:169], v[170:171] neg_lo:[0,1] neg_hi:[0,1]
	v_pk_add_f32 v[114:115], v[172:173], v[158:159]
	v_mov_b32_e32 v116, v124
	v_mov_b32_e32 v117, v125
	v_mov_b32_e32 v124, v160
	v_mov_b32_e32 v125, v161
;     __device__ __forceinline__ void operator()(f32x4 (&acc)[2][2][4][2], const Unit& u, int wr, int wc, int fr, int fq) const {
;     ...
;                 const int row = row0 + ai * HALF + m * 16;
;                 if (sec < 2 && wc == 0) {
;                     const f32x4 t0 = *(const f32x4*)(tab + (size_t)row * 32 + 8 * fq), t1 = *(const f32x4*)(tab + (size_t)row * 32 + 8 * fq + 4);
;                     const float cs[4] = {t0[0], t0[2], t1[0], t1[2]}, sn[4] = {t0[1], t0[3], t1[1], t1[3]};
; #pragma unroll
;                     for (int bj = 0; bj < 2; ++bj)
; #pragma unroll
;                         for (int j = 0; j < 4; ++j) { const float a = acc[ai][bj][m][0][j], b = acc[ai][bj][m][1][j];
;                             acc[ai][bj][m][0][j] = a * cs[j] - b * sn[j]; acc[ai][bj][m][1][j] = b * cs[j] + a * sn[j]; }
;                 }
;                 bf16_t* rowp = O + (size_t)row * INC + col0;
; #pragma unroll
;                 for (int bj = 0; bj < 2; ++bj)
; #pragma unroll
;                     for (int n = 0; n < 2; ++n) { const f32x4 v = acc[ai][bj][m][n] * (scale * rt[u.i * 256 + wr * 64 + fr + ai * HALF + m * 16]); u32x2 w; w.x = pk2(v[0], v[1]); w.y = pk2(v[2], v[3]); *(u32x2*)(rowp + bj * HALF + n * 16) = w; }
.LBB0_750:
	s_cmp_lt_u32 s47, 8
	s_cselect_b64 vcc, -1, 0
	s_lshl_b32 s11, s46, 10
	v_add_u32_e32 v154, s11, v149
	ds_read_b32 v155, v154
	v_cndmask_b32_e32 v145, 1.0, v153, vcc
	v_lshl_or_b32 v142, s47, 8, v148
	v_mov_b64_e32 v[156:157], s[72:73]
	v_ashrrev_i32_e32 v143, 31, v142
	s_waitcnt lgkmcnt(0)
	v_mul_f32_e32 v158, v145, v155
	v_mad_i64_i32 v[156:157], s[18:19], v144, s43, v[156:157]
	v_pk_mul_f32 v[114:115], v[114:115], v[158:159] op_sel_hi:[1,0]
	v_pk_mul_f32 v[112:113], v[112:113], v[158:159] op_sel_hi:[1,0]
	v_lshl_add_u64 v[156:157], v[142:143], 1, v[156:157]
	v_cvt_pk_bf16_f32 v112, v112, v113
	v_cvt_pk_bf16_f32 v113, v114, v115
	v_pk_mul_f32 v[126:127], v[126:127], v[158:159] op_sel_hi:[1,0]
	v_pk_mul_f32 v[124:125], v[124:125], v[158:159] op_sel_hi:[1,0]
	v_pk_mul_f32 v[122:123], v[122:123], v[158:159] op_sel_hi:[1,0]
	v_pk_mul_f32 v[120:121], v[120:121], v[158:159] op_sel_hi:[1,0]
	v_pk_mul_f32 v[118:119], v[118:119], v[158:159] op_sel_hi:[1,0]
	v_pk_mul_f32 v[116:117], v[116:117], v[158:159] op_sel_hi:[1,0]
	v_cvt_pk_bf16_f32 v124, v124, v125
	v_cvt_pk_bf16_f32 v125, v126, v127
	v_cvt_pk_bf16_f32 v120, v120, v121
	v_cvt_pk_bf16_f32 v121, v122, v123
	v_cvt_pk_bf16_f32 v116, v116, v117
	v_cvt_pk_bf16_f32 v117, v118, v119
	s_and_b64 vcc, exec, s[4:5]
	s_nop 1
	v_permlane16_swap_b32_e32 v124, v120
	v_permlane16_swap_b32_e32 v125, v121
	v_permlane16_swap_b32_e32 v116, v112
	v_permlane16_swap_b32_e32 v117, v113
	v_mov_b32_e32 v126, v120
	v_mov_b32_e32 v127, v121
	v_mov_b32_e32 v118, v112
	v_mov_b32_e32 v119, v113
	v_lshl_add_u64 v[246:247], v[156:157], 0, v[244:245]
	global_store_dwordx4 v[246:247], v[124:127], off
	global_store_dwordx4 v[246:247], v[116:119], off offset:256
	v_or_b32_e32 v112, 16, v144
	v_ashrrev_i32_e32 v113, 31, v112
	s_cbranch_vccnz .LBB0_752
	s_waitcnt vmcnt(14)
	v_mov_b32_e32 v114, v186
	v_mov_b32_e32 v115, v187
	v_mov_b32_e32 v116, v188
	v_mov_b32_e32 v117, v189
	v_mov_b32_e32 v118, v190
	v_mov_b32_e32 v119, v191
	v_mov_b32_e32 v120, v192
	v_mov_b32_e32 v121, v193
	v_mov_b32_e32 v122, v114
	v_mov_b32_e32 v123, v116
	v_mov_b32_e32 v116, v115
	v_mul_f32_e32 v114, v110, v118
	v_mul_f32_e32 v124, v106, v119
	v_mul_f32_e32 v126, v106, v118
	v_mul_f32_e32 v156, v110, v119
	v_mov_b32_e32 v106, v111
	v_mov_b32_e32 v110, v107
	v_mul_f32_e32 v158, v102, v118
	v_mul_f32_e32 v160, v98, v119
	v_mul_f32_e32 v118, v98, v118
	v_mul_f32_e32 v162, v102, v119
	v_mov_b32_e32 v98, v103
	v_mov_b32_e32 v102, v99
	v_pk_mul_f32 v[164:165], v[104:105], v[116:117]
	v_pk_mul_f32 v[104:105], v[104:105], v[122:123]
	v_pk_mul_f32 v[106:107], v[106:107], v[120:121]
	v_pk_mul_f32 v[110:111], v[110:111], v[120:121]
	v_pk_mul_f32 v[166:167], v[96:97], v[116:117]
	v_pk_mul_f32 v[98:99], v[98:99], v[120:121]
	v_pk_mul_f32 v[102:103], v[102:103], v[120:121]
	v_pk_mul_f32 v[96:97], v[96:97], v[122:123]
	v_mov_b32_e32 v115, v106
	v_mov_b32_e32 v125, v107
	v_pk_fma_f32 v[120:121], v[108:109], v[122:123], v[164:165] neg_lo:[0,0,1] neg_hi:[0,0,1]
	v_mov_b32_e32 v157, v111
	v_mov_b32_e32 v127, v110
	v_pk_fma_f32 v[104:105], v[108:109], v[116:117], v[104:105]
	v_mov_b32_e32 v159, v98
	v_mov_b32_e32 v161, v99
	v_pk_fma_f32 v[108:109], v[100:101], v[122:123], v[166:167] neg_lo:[0,0,1] neg_hi:[0,0,1]
	v_mov_b32_e32 v163, v103
	v_mov_b32_e32 v119, v102
	v_pk_fma_f32 v[96:97], v[100:101], v[116:117], v[96:97]
	v_pk_add_f32 v[110:111], v[114:115], v[124:125] neg_lo:[0,1] neg_hi:[0,1]
	v_pk_add_f32 v[106:107], v[156:157], v[126:127]
	v_pk_add_f32 v[102:103], v[158:159], v[160:161] neg_lo:[0,1] neg_hi:[0,1]
	v_pk_add_f32 v[98:99], v[162:163], v[118:119]
	v_mov_b32_e32 v100, v108
	v_mov_b32_e32 v101, v109
	v_mov_b32_e32 v108, v120
	v_mov_b32_e32 v109, v121
.LBB0_752:
	ds_read_b32 v116, v154 offset:64
	v_mov_b64_e32 v[114:115], s[72:73]
	v_mad_i64_i32 v[112:113], s[18:19], v112, s43, v[114:115]
	v_lshl_add_u64 v[112:113], v[142:143], 1, v[112:113]
	s_waitcnt lgkmcnt(0)
	v_mul_f32_e32 v114, v145, v116
	v_pk_mul_f32 v[98:99], v[98:99], v[114:115] op_sel_hi:[1,0]
	v_pk_mul_f32 v[96:97], v[96:97], v[114:115] op_sel_hi:[1,0]
	v_pk_mul_f32 v[110:111], v[110:111], v[114:115] op_sel_hi:[1,0]
	v_cvt_pk_bf16_f32 v96, v96, v97
	v_cvt_pk_bf16_f32 v97, v98, v99
	v_pk_mul_f32 v[108:109], v[108:109], v[114:115] op_sel_hi:[1,0]
	v_pk_mul_f32 v[106:107], v[106:107], v[114:115] op_sel_hi:[1,0]
	v_pk_mul_f32 v[104:105], v[104:105], v[114:115] op_sel_hi:[1,0]
	v_pk_mul_f32 v[102:103], v[102:103], v[114:115] op_sel_hi:[1,0]
	v_pk_mul_f32 v[100:101], v[100:101], v[114:115] op_sel_hi:[1,0]
	v_cvt_pk_bf16_f32 v108, v108, v109
	v_cvt_pk_bf16_f32 v109, v110, v111
	v_cvt_pk_bf16_f32 v104, v104, v105
	v_cvt_pk_bf16_f32 v105, v106, v107
	v_cvt_pk_bf16_f32 v100, v100, v101
	v_cvt_pk_bf16_f32 v101, v102, v103
	s_and_b64 vcc, exec, s[4:5]
	s_nop 1
	v_permlane16_swap_b32_e32 v108, v104
	v_permlane16_swap_b32_e32 v109, v105
	v_permlane16_swap_b32_e32 v100, v96
	v_permlane16_swap_b32_e32 v101, v97
	v_mov_b32_e32 v110, v104
	v_mov_b32_e32 v111, v105
	v_mov_b32_e32 v102, v96
	v_mov_b32_e32 v103, v97
	v_lshl_add_u64 v[246:247], v[112:113], 0, v[244:245]
	global_store_dwordx4 v[246:247], v[108:111], off
	global_store_dwordx4 v[246:247], v[100:103], off offset:256
	v_or_b32_e32 v96, 32, v144
	v_ashrrev_i32_e32 v97, 31, v96
	s_cbranch_vccnz .LBB0_754
;     __device__ __forceinline__ void operator()(f32x4 (&acc)[2][2][4][2], const Unit& u, int wr, int wc, int fr, int fq) const {
;     ...
;                 const int row = row0 + ai * HALF + m * 16;
;                 if (sec < 2 && wc == 0) {
;                     const f32x4 t0 = *(const f32x4*)(tab + (size_t)row * 32 + 8 * fq), t1 = *(const f32x4*)(tab + (size_t)row * 32 + 8 * fq + 4);
;                     const float cs[4] = {t0[0], t0[2], t1[0], t1[2]}, sn[4] = {t0[1], t0[3], t1[1], t1[3]};
; #pragma unroll
;                     for (int bj = 0; bj < 2; ++bj)
; #pragma unroll
;                         for (int j = 0; j < 4; ++j) { const float a = acc[ai][bj][m][0][j], b = acc[ai][bj][m][1][j];
;                             acc[ai][bj][m][0][j] = a * cs[j] - b * sn[j]; acc[ai][bj][m][1][j] = b * cs[j] + a * sn[j]; }
;                 }
;                 bf16_t* rowp = O + (size_t)row * INC + col0;
; #pragma unroll
;                 for (int bj = 0; bj < 2; ++bj)
; #pragma unroll
;                     for (int n = 0; n < 2; ++n) { const f32x4 v = acc[ai][bj][m][n] * (scale * rt[u.i * 256 + wr * 64 + fr + ai * HALF + m * 16]); u32x2 w; w.x = pk2(v[0], v[1]); w.y = pk2(v[2], v[3]); *(u32x2*)(rowp + bj * HALF + n * 16) = w; }
	s_waitcnt vmcnt(14)
	v_mov_b32_e32 v98, v194
	v_mov_b32_e32 v99, v195
	v_mov_b32_e32 v100, v196
	v_mov_b32_e32 v101, v197
	v_mov_b32_e32 v102, v198
	v_mov_b32_e32 v103, v199
	v_mov_b32_e32 v104, v200
	v_mov_b32_e32 v105, v201
	v_mov_b32_e32 v106, v98
	v_mov_b32_e32 v107, v100
	v_mov_b32_e32 v100, v99
	v_mul_f32_e32 v98, v94, v102
	v_mul_f32_e32 v108, v90, v103
	v_mul_f32_e32 v110, v90, v102
	v_mul_f32_e32 v112, v94, v103
	v_mov_b32_e32 v90, v95
	v_mov_b32_e32 v94, v91
	v_mul_f32_e32 v114, v86, v102
	v_mul_f32_e32 v116, v82, v103
	v_mul_f32_e32 v102, v82, v102
	v_mul_f32_e32 v118, v86, v103
	v_mov_b32_e32 v82, v87
	v_mov_b32_e32 v86, v83
	v_pk_mul_f32 v[120:121], v[88:89], v[100:101]
	v_pk_mul_f32 v[88:89], v[88:89], v[106:107]
	v_pk_mul_f32 v[90:91], v[90:91], v[104:105]
	v_pk_mul_f32 v[94:95], v[94:95], v[104:105]
	v_pk_mul_f32 v[122:123], v[80:81], v[100:101]
	v_pk_mul_f32 v[82:83], v[82:83], v[104:105]
	v_pk_mul_f32 v[86:87], v[86:87], v[104:105]
	v_pk_mul_f32 v[80:81], v[80:81], v[106:107]
	v_mov_b32_e32 v99, v90
	v_mov_b32_e32 v109, v91
	v_pk_fma_f32 v[104:105], v[92:93], v[106:107], v[120:121] neg_lo:[0,0,1] neg_hi:[0,0,1]
	v_mov_b32_e32 v113, v95
	v_mov_b32_e32 v111, v94
	v_pk_fma_f32 v[88:89], v[92:93], v[100:101], v[88:89]
	v_mov_b32_e32 v115, v82
	v_mov_b32_e32 v117, v83
	v_pk_fma_f32 v[92:93], v[84:85], v[106:107], v[122:123] neg_lo:[0,0,1] neg_hi:[0,0,1]
	v_mov_b32_e32 v119, v87
	v_mov_b32_e32 v103, v86
	v_pk_fma_f32 v[80:81], v[84:85], v[100:101], v[80:81]
	v_pk_add_f32 v[94:95], v[98:99], v[108:109] neg_lo:[0,1] neg_hi:[0,1]
	v_pk_add_f32 v[90:91], v[112:113], v[110:111]
	v_pk_add_f32 v[86:87], v[114:115], v[116:117] neg_lo:[0,1] neg_hi:[0,1]
	v_pk_add_f32 v[82:83], v[118:119], v[102:103]
	v_mov_b32_e32 v84, v92
	v_mov_b32_e32 v85, v93
	v_mov_b32_e32 v92, v104
	v_mov_b32_e32 v93, v105
.LBB0_754:
	ds_read_b32 v100, v154 offset:128
	v_mov_b64_e32 v[98:99], s[72:73]
	v_mad_i64_i32 v[96:97], s[18:19], v96, s43, v[98:99]
	v_lshl_add_u64 v[96:97], v[142:143], 1, v[96:97]
	s_waitcnt lgkmcnt(0)
	v_mul_f32_e32 v98, v145, v100
	v_pk_mul_f32 v[82:83], v[82:83], v[98:99] op_sel_hi:[1,0]
	v_pk_mul_f32 v[80:81], v[80:81], v[98:99] op_sel_hi:[1,0]
	v_pk_mul_f32 v[94:95], v[94:95], v[98:99] op_sel_hi:[1,0]
	v_cvt_pk_bf16_f32 v80, v80, v81
	v_cvt_pk_bf16_f32 v81, v82, v83
	v_pk_mul_f32 v[92:93], v[92:93], v[98:99] op_sel_hi:[1,0]
	v_pk_mul_f32 v[90:91], v[90:91], v[98:99] op_sel_hi:[1,0]
	v_pk_mul_f32 v[88:89], v[88:89], v[98:99] op_sel_hi:[1,0]
	v_pk_mul_f32 v[86:87], v[86:87], v[98:99] op_sel_hi:[1,0]
	v_pk_mul_f32 v[84:85], v[84:85], v[98:99] op_sel_hi:[1,0]
	v_cvt_pk_bf16_f32 v92, v92, v93
	v_cvt_pk_bf16_f32 v93, v94, v95
	v_cvt_pk_bf16_f32 v88, v88, v89
	v_cvt_pk_bf16_f32 v89, v90, v91
	v_cvt_pk_bf16_f32 v84, v84, v85
	v_cvt_pk_bf16_f32 v85, v86, v87
	s_and_b64 vcc, exec, s[4:5]
	s_nop 1
	v_permlane16_swap_b32_e32 v92, v88
	v_permlane16_swap_b32_e32 v93, v89
	v_permlane16_swap_b32_e32 v84, v80
	v_permlane16_swap_b32_e32 v85, v81
	v_mov_b32_e32 v94, v88
	v_mov_b32_e32 v95, v89
	v_mov_b32_e32 v86, v80
	v_mov_b32_e32 v87, v81
	v_lshl_add_u64 v[246:247], v[96:97], 0, v[244:245]
	global_store_dwordx4 v[246:247], v[92:95], off
	global_store_dwordx4 v[246:247], v[84:87], off offset:256
	v_or_b32_e32 v80, 48, v144
	v_ashrrev_i32_e32 v81, 31, v80
	s_cbranch_vccnz .LBB0_756
	s_waitcnt vmcnt(14)
	v_mov_b32_e32 v82, v202
	v_mov_b32_e32 v83, v203
	v_mov_b32_e32 v84, v204
	v_mov_b32_e32 v85, v205
	v_mov_b32_e32 v86, v206
	v_mov_b32_e32 v87, v207
	v_mov_b32_e32 v88, v208
	v_mov_b32_e32 v89, v209
	v_mov_b32_e32 v90, v82
	v_mov_b32_e32 v91, v84
	v_mov_b32_e32 v84, v83
	v_mul_f32_e32 v82, v78, v86
	v_mul_f32_e32 v92, v74, v87
	v_mul_f32_e32 v94, v74, v86
	v_mul_f32_e32 v96, v78, v87
	v_mov_b32_e32 v74, v79
	v_mov_b32_e32 v78, v75
	v_mul_f32_e32 v98, v70, v86
	v_mul_f32_e32 v100, v66, v87
	v_mul_f32_e32 v86, v66, v86
	v_mul_f32_e32 v102, v70, v87
	v_mov_b32_e32 v66, v71
	v_mov_b32_e32 v70, v67
	v_pk_mul_f32 v[104:105], v[72:73], v[84:85]
	v_pk_mul_f32 v[72:73], v[72:73], v[90:91]
	v_pk_mul_f32 v[74:75], v[74:75], v[88:89]
	v_pk_mul_f32 v[78:79], v[78:79], v[88:89]
	v_pk_mul_f32 v[106:107], v[64:65], v[84:85]
	v_pk_mul_f32 v[66:67], v[66:67], v[88:89]
	v_pk_mul_f32 v[70:71], v[70:71], v[88:89]
	v_pk_mul_f32 v[64:65], v[64:65], v[90:91]
	v_mov_b32_e32 v83, v74
	v_mov_b32_e32 v93, v75
	v_pk_fma_f32 v[88:89], v[76:77], v[90:91], v[104:105] neg_lo:[0,0,1] neg_hi:[0,0,1]
	v_mov_b32_e32 v97, v79
	v_mov_b32_e32 v95, v78
	v_pk_fma_f32 v[72:73], v[76:77], v[84:85], v[72:73]
	v_mov_b32_e32 v99, v66
	v_mov_b32_e32 v101, v67
	v_pk_fma_f32 v[76:77], v[68:69], v[90:91], v[106:107] neg_lo:[0,0,1] neg_hi:[0,0,1]
	v_mov_b32_e32 v103, v71
	v_mov_b32_e32 v87, v70
	v_pk_fma_f32 v[64:65], v[68:69], v[84:85], v[64:65]
	v_pk_add_f32 v[78:79], v[82:83], v[92:93] neg_lo:[0,1] neg_hi:[0,1]
	v_pk_add_f32 v[74:75], v[96:97], v[94:95]
	v_pk_add_f32 v[70:71], v[98:99], v[100:101] neg_lo:[0,1] neg_hi:[0,1]
	v_pk_add_f32 v[66:67], v[102:103], v[86:87]
	v_mov_b32_e32 v68, v76
	v_mov_b32_e32 v69, v77
	v_mov_b32_e32 v76, v88
	v_mov_b32_e32 v77, v89
;     __device__ __forceinline__ void operator()(f32x4 (&acc)[2][2][4][2], const Unit& u, int wr, int wc, int fr, int fq) const {
;     ...
;                 const int row = row0 + ai * HALF + m * 16;
;                 if (sec < 2 && wc == 0) {
;                     const f32x4 t0 = *(const f32x4*)(tab + (size_t)row * 32 + 8 * fq), t1 = *(const f32x4*)(tab + (size_t)row * 32 + 8 * fq + 4);
;                     const float cs[4] = {t0[0], t0[2], t1[0], t1[2]}, sn[4] = {t0[1], t0[3], t1[1], t1[3]};
; #pragma unroll
;                     for (int bj = 0; bj < 2; ++bj)
; #pragma unroll
;                         for (int j = 0; j < 4; ++j) { const float a = acc[ai][bj][m][0][j], b = acc[ai][bj][m][1][j];
;                             acc[ai][bj][m][0][j] = a * cs[j] - b * sn[j]; acc[ai][bj][m][1][j] = b * cs[j] + a * sn[j]; }
;                 }
;                 bf16_t* rowp = O + (size_t)row * INC + col0;
; #pragma unroll
;                 for (int bj = 0; bj < 2; ++bj)
; #pragma unroll
;                     for (int n = 0; n < 2; ++n) { const f32x4 v = acc[ai][bj][m][n] * (scale * rt[u.i * 256 + wr * 64 + fr + ai * HALF + m * 16]); u32x2 w; w.x = pk2(v[0], v[1]); w.y = pk2(v[2], v[3]); *(u32x2*)(rowp + bj * HALF + n * 16) = w; }
.LBB0_756:
	ds_read_b32 v84, v154 offset:192
	v_mov_b64_e32 v[82:83], s[72:73]
	v_mad_i64_i32 v[80:81], s[18:19], v80, s43, v[82:83]
	v_lshl_add_u64 v[80:81], v[142:143], 1, v[80:81]
	s_waitcnt lgkmcnt(0)
	v_mul_f32_e32 v82, v145, v84
	v_pk_mul_f32 v[66:67], v[66:67], v[82:83] op_sel_hi:[1,0]
	v_pk_mul_f32 v[64:65], v[64:65], v[82:83] op_sel_hi:[1,0]
	v_pk_mul_f32 v[78:79], v[78:79], v[82:83] op_sel_hi:[1,0]
	v_cvt_pk_bf16_f32 v64, v64, v65
	v_cvt_pk_bf16_f32 v65, v66, v67
	v_pk_mul_f32 v[76:77], v[76:77], v[82:83] op_sel_hi:[1,0]
	v_pk_mul_f32 v[74:75], v[74:75], v[82:83] op_sel_hi:[1,0]
	v_pk_mul_f32 v[72:73], v[72:73], v[82:83] op_sel_hi:[1,0]
	v_pk_mul_f32 v[70:71], v[70:71], v[82:83] op_sel_hi:[1,0]
	v_pk_mul_f32 v[68:69], v[68:69], v[82:83] op_sel_hi:[1,0]
	v_cvt_pk_bf16_f32 v76, v76, v77
	v_cvt_pk_bf16_f32 v77, v78, v79
	v_cvt_pk_bf16_f32 v72, v72, v73
	v_cvt_pk_bf16_f32 v73, v74, v75
	v_cvt_pk_bf16_f32 v68, v68, v69
	v_cvt_pk_bf16_f32 v69, v70, v71
	s_and_b64 vcc, exec, s[4:5]
	s_nop 1
	v_permlane16_swap_b32_e32 v76, v72
	v_permlane16_swap_b32_e32 v77, v73
	v_permlane16_swap_b32_e32 v68, v64
	v_permlane16_swap_b32_e32 v69, v65
	v_mov_b32_e32 v78, v72
	v_mov_b32_e32 v79, v73
	v_mov_b32_e32 v70, v64
	v_mov_b32_e32 v71, v65
	v_lshl_add_u64 v[246:247], v[80:81], 0, v[244:245]
	global_store_dwordx4 v[246:247], v[76:79], off
	global_store_dwordx4 v[246:247], v[68:71], off offset:256
	v_add_u32_e32 v64, 0x80, v144
	v_ashrrev_i32_e32 v65, 31, v64
	s_cbranch_vccnz .LBB0_758
	s_waitcnt vmcnt(14)
	v_mov_b32_e32 v66, v210
	v_mov_b32_e32 v67, v211
	v_mov_b32_e32 v68, v212
	v_mov_b32_e32 v69, v213
	v_mov_b32_e32 v70, v214
	v_mov_b32_e32 v71, v215
	v_mov_b32_e32 v72, v216
	v_mov_b32_e32 v73, v217
	v_mov_b32_e32 v74, v66
	v_mov_b32_e32 v75, v68
	v_mov_b32_e32 v68, v67
	v_mul_f32_e32 v66, v62, v70
	v_mul_f32_e32 v76, v58, v71
	v_mul_f32_e32 v78, v58, v70
	v_mul_f32_e32 v80, v62, v71
	v_mov_b32_e32 v58, v63
	v_mov_b32_e32 v62, v59
	v_mul_f32_e32 v82, v54, v70
	v_mul_f32_e32 v84, v50, v71
	v_mul_f32_e32 v70, v50, v70
	v_mul_f32_e32 v86, v54, v71
	v_mov_b32_e32 v50, v55
	v_mov_b32_e32 v54, v51
	v_pk_mul_f32 v[88:89], v[56:57], v[68:69]
	v_pk_mul_f32 v[56:57], v[56:57], v[74:75]
	v_pk_mul_f32 v[58:59], v[58:59], v[72:73]
	v_pk_mul_f32 v[62:63], v[62:63], v[72:73]
	v_pk_mul_f32 v[90:91], v[48:49], v[68:69]
	v_pk_mul_f32 v[50:51], v[50:51], v[72:73]
	v_pk_mul_f32 v[54:55], v[54:55], v[72:73]
	v_pk_mul_f32 v[48:49], v[48:49], v[74:75]
	v_mov_b32_e32 v67, v58
	v_mov_b32_e32 v77, v59
	v_pk_fma_f32 v[72:73], v[60:61], v[74:75], v[88:89] neg_lo:[0,0,1] neg_hi:[0,0,1]
	v_mov_b32_e32 v81, v63
	v_mov_b32_e32 v79, v62
	v_pk_fma_f32 v[56:57], v[60:61], v[68:69], v[56:57]
	v_mov_b32_e32 v83, v50
	v_mov_b32_e32 v85, v51
	v_pk_fma_f32 v[60:61], v[52:53], v[74:75], v[90:91] neg_lo:[0,0,1] neg_hi:[0,0,1]
	v_mov_b32_e32 v87, v55
	v_mov_b32_e32 v71, v54
	v_pk_fma_f32 v[48:49], v[52:53], v[68:69], v[48:49]
	v_pk_add_f32 v[62:63], v[66:67], v[76:77] neg_lo:[0,1] neg_hi:[0,1]
	v_pk_add_f32 v[58:59], v[80:81], v[78:79]
	v_pk_add_f32 v[54:55], v[82:83], v[84:85] neg_lo:[0,1] neg_hi:[0,1]
	v_pk_add_f32 v[50:51], v[86:87], v[70:71]
	v_mov_b32_e32 v52, v60
	v_mov_b32_e32 v53, v61
	v_mov_b32_e32 v60, v72
	v_mov_b32_e32 v61, v73
.LBB0_758:
	ds_read_b32 v68, v154 offset:512
	v_mov_b64_e32 v[66:67], s[72:73]
	v_mad_i64_i32 v[64:65], s[18:19], v64, s43, v[66:67]
	v_lshl_add_u64 v[64:65], v[142:143], 1, v[64:65]
	s_waitcnt lgkmcnt(0)
	v_mul_f32_e32 v66, v145, v68
	v_pk_mul_f32 v[50:51], v[50:51], v[66:67] op_sel_hi:[1,0]
	v_pk_mul_f32 v[48:49], v[48:49], v[66:67] op_sel_hi:[1,0]
	v_pk_mul_f32 v[62:63], v[62:63], v[66:67] op_sel_hi:[1,0]
	v_cvt_pk_bf16_f32 v48, v48, v49
	v_cvt_pk_bf16_f32 v49, v50, v51
	v_pk_mul_f32 v[60:61], v[60:61], v[66:67] op_sel_hi:[1,0]
	v_pk_mul_f32 v[58:59], v[58:59], v[66:67] op_sel_hi:[1,0]
	v_pk_mul_f32 v[56:57], v[56:57], v[66:67] op_sel_hi:[1,0]
	v_pk_mul_f32 v[54:55], v[54:55], v[66:67] op_sel_hi:[1,0]
	v_pk_mul_f32 v[52:53], v[52:53], v[66:67] op_sel_hi:[1,0]
	v_cvt_pk_bf16_f32 v60, v60, v61
	v_cvt_pk_bf16_f32 v61, v62, v63
	v_cvt_pk_bf16_f32 v56, v56, v57
	v_cvt_pk_bf16_f32 v57, v58, v59
	v_cvt_pk_bf16_f32 v52, v52, v53
	v_cvt_pk_bf16_f32 v53, v54, v55
	s_and_b64 vcc, exec, s[4:5]
	s_nop 1
	v_permlane16_swap_b32_e32 v60, v56
	v_permlane16_swap_b32_e32 v61, v57
	v_permlane16_swap_b32_e32 v52, v48
	v_permlane16_swap_b32_e32 v53, v49
	v_mov_b32_e32 v62, v56
	v_mov_b32_e32 v63, v57
	v_mov_b32_e32 v54, v48
	v_mov_b32_e32 v55, v49
	v_lshl_add_u64 v[246:247], v[64:65], 0, v[244:245]
	global_store_dwordx4 v[246:247], v[60:63], off
	global_store_dwordx4 v[246:247], v[52:55], off offset:256
	v_add_u32_e32 v48, 0x90, v144
	v_ashrrev_i32_e32 v49, 31, v48
	s_cbranch_vccnz .LBB0_760
	s_waitcnt vmcnt(14)
	v_mov_b32_e32 v50, v218
	v_mov_b32_e32 v51, v219
	v_mov_b32_e32 v52, v220
	v_mov_b32_e32 v53, v221
	v_mov_b32_e32 v54, v222
	v_mov_b32_e32 v55, v223
	v_mov_b32_e32 v56, v224
	v_mov_b32_e32 v57, v225
	v_mov_b32_e32 v58, v50
	v_mov_b32_e32 v59, v52
	v_mov_b32_e32 v52, v51
	v_mul_f32_e32 v50, v46, v54
	v_mul_f32_e32 v60, v42, v55
	v_mul_f32_e32 v62, v42, v54
	v_mul_f32_e32 v64, v46, v55
	v_mov_b32_e32 v42, v47
	v_mov_b32_e32 v46, v43
	v_mul_f32_e32 v66, v38, v54
	v_mul_f32_e32 v68, v34, v55
	v_mul_f32_e32 v54, v34, v54
	v_mul_f32_e32 v70, v38, v55
	v_mov_b32_e32 v34, v39
	v_mov_b32_e32 v38, v35
	v_pk_mul_f32 v[72:73], v[40:41], v[52:53]
	v_pk_mul_f32 v[40:41], v[40:41], v[58:59]
	v_pk_mul_f32 v[42:43], v[42:43], v[56:57]
	v_pk_mul_f32 v[46:47], v[46:47], v[56:57]
	v_pk_mul_f32 v[74:75], v[32:33], v[52:53]
	v_pk_mul_f32 v[34:35], v[34:35], v[56:57]
	v_pk_mul_f32 v[38:39], v[38:39], v[56:57]
	v_pk_mul_f32 v[32:33], v[32:33], v[58:59]
	v_mov_b32_e32 v51, v42
	v_mov_b32_e32 v61, v43
	v_pk_fma_f32 v[56:57], v[44:45], v[58:59], v[72:73] neg_lo:[0,0,1] neg_hi:[0,0,1]
	v_mov_b32_e32 v65, v47
	v_mov_b32_e32 v63, v46
	v_pk_fma_f32 v[40:41], v[44:45], v[52:53], v[40:41]
	v_mov_b32_e32 v67, v34
	v_mov_b32_e32 v69, v35
	v_pk_fma_f32 v[44:45], v[36:37], v[58:59], v[74:75] neg_lo:[0,0,1] neg_hi:[0,0,1]
	v_mov_b32_e32 v71, v39
	v_mov_b32_e32 v55, v38
	v_pk_fma_f32 v[32:33], v[36:37], v[52:53], v[32:33]
	v_pk_add_f32 v[46:47], v[50:51], v[60:61] neg_lo:[0,1] neg_hi:[0,1]
	v_pk_add_f32 v[42:43], v[64:65], v[62:63]
	v_pk_add_f32 v[38:39], v[66:67], v[68:69] neg_lo:[0,1] neg_hi:[0,1]
	v_pk_add_f32 v[34:35], v[70:71], v[54:55]
	v_mov_b32_e32 v36, v44
	v_mov_b32_e32 v37, v45
	v_mov_b32_e32 v44, v56
	v_mov_b32_e32 v45, v57
;     __device__ __forceinline__ void operator()(f32x4 (&acc)[2][2][4][2], const Unit& u, int wr, int wc, int fr, int fq) const {
;     ...
;                 const int row = row0 + ai * HALF + m * 16;
;                 if (sec < 2 && wc == 0) {
;                     const f32x4 t0 = *(const f32x4*)(tab + (size_t)row * 32 + 8 * fq), t1 = *(const f32x4*)(tab + (size_t)row * 32 + 8 * fq + 4);
;                     const float cs[4] = {t0[0], t0[2], t1[0], t1[2]}, sn[4] = {t0[1], t0[3], t1[1], t1[3]};
; #pragma unroll
;                     for (int bj = 0; bj < 2; ++bj)
; #pragma unroll
;                         for (int j = 0; j < 4; ++j) { const float a = acc[ai][bj][m][0][j], b = acc[ai][bj][m][1][j];
;                             acc[ai][bj][m][0][j] = a * cs[j] - b * sn[j]; acc[ai][bj][m][1][j] = b * cs[j] + a * sn[j]; }
;                 }
;                 bf16_t* rowp = O + (size_t)row * INC + col0;
; #pragma unroll
;                 for (int bj = 0; bj < 2; ++bj)
; #pragma unroll
;                     for (int n = 0; n < 2; ++n) { const f32x4 v = acc[ai][bj][m][n] * (scale * rt[u.i * 256 + wr * 64 + fr + ai * HALF + m * 16]); u32x2 w; w.x = pk2(v[0], v[1]); w.y = pk2(v[2], v[3]); *(u32x2*)(rowp + bj * HALF + n * 16) = w; }
.LBB0_760:
	ds_read_b32 v52, v154 offset:576
	v_mov_b64_e32 v[50:51], s[72:73]
	v_mad_i64_i32 v[48:49], s[18:19], v48, s43, v[50:51]
	v_lshl_add_u64 v[48:49], v[142:143], 1, v[48:49]
	s_waitcnt lgkmcnt(0)
	v_mul_f32_e32 v50, v145, v52
	v_pk_mul_f32 v[34:35], v[34:35], v[50:51] op_sel_hi:[1,0]
	v_pk_mul_f32 v[32:33], v[32:33], v[50:51] op_sel_hi:[1,0]
	v_pk_mul_f32 v[46:47], v[46:47], v[50:51] op_sel_hi:[1,0]
	v_cvt_pk_bf16_f32 v32, v32, v33
	v_cvt_pk_bf16_f32 v33, v34, v35
	v_pk_mul_f32 v[44:45], v[44:45], v[50:51] op_sel_hi:[1,0]
	v_pk_mul_f32 v[42:43], v[42:43], v[50:51] op_sel_hi:[1,0]
	v_pk_mul_f32 v[40:41], v[40:41], v[50:51] op_sel_hi:[1,0]
	v_pk_mul_f32 v[38:39], v[38:39], v[50:51] op_sel_hi:[1,0]
	v_pk_mul_f32 v[36:37], v[36:37], v[50:51] op_sel_hi:[1,0]
	v_cvt_pk_bf16_f32 v44, v44, v45
	v_cvt_pk_bf16_f32 v45, v46, v47
	v_cvt_pk_bf16_f32 v40, v40, v41
	v_cvt_pk_bf16_f32 v41, v42, v43
	v_cvt_pk_bf16_f32 v36, v36, v37
	v_cvt_pk_bf16_f32 v37, v38, v39
	s_and_b64 vcc, exec, s[4:5]
	s_nop 1
	v_permlane16_swap_b32_e32 v44, v40
	v_permlane16_swap_b32_e32 v45, v41
	v_permlane16_swap_b32_e32 v36, v32
	v_permlane16_swap_b32_e32 v37, v33
	v_mov_b32_e32 v46, v40
	v_mov_b32_e32 v47, v41
	v_mov_b32_e32 v38, v32
	v_mov_b32_e32 v39, v33
	v_lshl_add_u64 v[246:247], v[48:49], 0, v[244:245]
	global_store_dwordx4 v[246:247], v[44:47], off
	global_store_dwordx4 v[246:247], v[36:39], off offset:256
	v_add_u32_e32 v32, 0xa0, v144
	v_ashrrev_i32_e32 v33, 31, v32
	s_cbranch_vccnz .LBB0_762
	s_waitcnt vmcnt(14)
	v_mov_b32_e32 v34, v226
	v_mov_b32_e32 v35, v227
	v_mov_b32_e32 v36, v228
	v_mov_b32_e32 v37, v229
	v_mov_b32_e32 v38, v230
	v_mov_b32_e32 v39, v231
	v_mov_b32_e32 v40, v232
	v_mov_b32_e32 v41, v233
	v_mov_b32_e32 v42, v34
	v_mov_b32_e32 v43, v36
	v_mov_b32_e32 v36, v35
	v_mul_f32_e32 v34, v30, v38
	v_mul_f32_e32 v44, v26, v39
	v_mul_f32_e32 v46, v26, v38
	v_mul_f32_e32 v48, v30, v39
	v_mov_b32_e32 v26, v31
	v_mov_b32_e32 v30, v27
	v_mul_f32_e32 v50, v22, v38
	v_mul_f32_e32 v52, v18, v39
	v_mul_f32_e32 v38, v18, v38
	v_mul_f32_e32 v54, v22, v39
	v_mov_b32_e32 v18, v23
	v_mov_b32_e32 v22, v19
	v_pk_mul_f32 v[56:57], v[24:25], v[36:37]
	v_pk_mul_f32 v[24:25], v[24:25], v[42:43]
	v_pk_mul_f32 v[26:27], v[26:27], v[40:41]
	v_pk_mul_f32 v[30:31], v[30:31], v[40:41]
	v_pk_mul_f32 v[58:59], v[16:17], v[36:37]
	v_pk_mul_f32 v[18:19], v[18:19], v[40:41]
	v_pk_mul_f32 v[22:23], v[22:23], v[40:41]
	v_pk_mul_f32 v[16:17], v[16:17], v[42:43]
	v_mov_b32_e32 v35, v26
	v_mov_b32_e32 v45, v27
	v_pk_fma_f32 v[40:41], v[28:29], v[42:43], v[56:57] neg_lo:[0,0,1] neg_hi:[0,0,1]
	v_mov_b32_e32 v49, v31
	v_mov_b32_e32 v47, v30
	v_pk_fma_f32 v[24:25], v[28:29], v[36:37], v[24:25]
	v_mov_b32_e32 v51, v18
	v_mov_b32_e32 v53, v19
	v_pk_fma_f32 v[28:29], v[20:21], v[42:43], v[58:59] neg_lo:[0,0,1] neg_hi:[0,0,1]
	v_mov_b32_e32 v55, v23
	v_mov_b32_e32 v39, v22
	v_pk_fma_f32 v[16:17], v[20:21], v[36:37], v[16:17]
	v_pk_add_f32 v[30:31], v[34:35], v[44:45] neg_lo:[0,1] neg_hi:[0,1]
	v_pk_add_f32 v[26:27], v[48:49], v[46:47]
	v_pk_add_f32 v[22:23], v[50:51], v[52:53] neg_lo:[0,1] neg_hi:[0,1]
	v_pk_add_f32 v[18:19], v[54:55], v[38:39]
	v_mov_b32_e32 v20, v28
	v_mov_b32_e32 v21, v29
	v_mov_b32_e32 v28, v40
	v_mov_b32_e32 v29, v41
.LBB0_762:
	ds_read_b32 v36, v154 offset:640
	v_mov_b64_e32 v[34:35], s[72:73]
	v_mad_i64_i32 v[32:33], s[18:19], v32, s43, v[34:35]
	v_lshl_add_u64 v[32:33], v[142:143], 1, v[32:33]
	s_waitcnt lgkmcnt(0)
	v_mul_f32_e32 v34, v145, v36
	v_pk_mul_f32 v[18:19], v[18:19], v[34:35] op_sel_hi:[1,0]
	v_pk_mul_f32 v[16:17], v[16:17], v[34:35] op_sel_hi:[1,0]
	v_pk_mul_f32 v[30:31], v[30:31], v[34:35] op_sel_hi:[1,0]
	v_cvt_pk_bf16_f32 v16, v16, v17
	v_cvt_pk_bf16_f32 v17, v18, v19
	v_pk_mul_f32 v[28:29], v[28:29], v[34:35] op_sel_hi:[1,0]
	v_pk_mul_f32 v[26:27], v[26:27], v[34:35] op_sel_hi:[1,0]
	v_pk_mul_f32 v[24:25], v[24:25], v[34:35] op_sel_hi:[1,0]
	v_pk_mul_f32 v[22:23], v[22:23], v[34:35] op_sel_hi:[1,0]
	v_pk_mul_f32 v[20:21], v[20:21], v[34:35] op_sel_hi:[1,0]
	v_cvt_pk_bf16_f32 v28, v28, v29
	v_cvt_pk_bf16_f32 v29, v30, v31
	v_cvt_pk_bf16_f32 v24, v24, v25
	v_cvt_pk_bf16_f32 v25, v26, v27
	v_cvt_pk_bf16_f32 v20, v20, v21
	v_cvt_pk_bf16_f32 v21, v22, v23
	s_and_b64 vcc, exec, s[4:5]
	s_nop 1
	v_permlane16_swap_b32_e32 v28, v24
	v_permlane16_swap_b32_e32 v29, v25
	v_permlane16_swap_b32_e32 v20, v16
	v_permlane16_swap_b32_e32 v21, v17
	v_mov_b32_e32 v30, v24
	v_mov_b32_e32 v31, v25
	v_mov_b32_e32 v22, v16
	v_mov_b32_e32 v23, v17
	v_lshl_add_u64 v[246:247], v[32:33], 0, v[244:245]
	global_store_dwordx4 v[246:247], v[28:31], off
	global_store_dwordx4 v[246:247], v[20:23], off offset:256
	v_add_u32_e32 v16, 0xb0, v144
	v_ashrrev_i32_e32 v17, 31, v16
	s_cbranch_vccnz .LBB0_743
	s_waitcnt vmcnt(14)
	v_mov_b32_e32 v18, v234
	v_mov_b32_e32 v19, v235
	v_mov_b32_e32 v20, v236
	v_mov_b32_e32 v21, v237
	v_mov_b32_e32 v22, v238
	v_mov_b32_e32 v23, v239
	v_mov_b32_e32 v24, v240
	v_mov_b32_e32 v25, v241
	v_mov_b32_e32 v26, v18
	v_mov_b32_e32 v27, v20
	v_mov_b32_e32 v20, v19
	v_mul_f32_e32 v18, v14, v22
	v_mul_f32_e32 v28, v10, v23
	v_mul_f32_e32 v30, v10, v22
	v_mul_f32_e32 v32, v14, v23
	v_mov_b32_e32 v10, v15
	v_mov_b32_e32 v14, v11
	v_mul_f32_e32 v34, v6, v22
	v_mul_f32_e32 v36, v2, v23
	v_mul_f32_e32 v22, v2, v22
	v_mul_f32_e32 v38, v6, v23
	v_mov_b32_e32 v2, v7
	v_mov_b32_e32 v6, v3
	v_pk_mul_f32 v[40:41], v[8:9], v[20:21]
	v_pk_mul_f32 v[8:9], v[8:9], v[26:27]
	v_pk_mul_f32 v[10:11], v[10:11], v[24:25]
	v_pk_mul_f32 v[14:15], v[14:15], v[24:25]
	v_pk_mul_f32 v[42:43], v[0:1], v[20:21]
	v_pk_mul_f32 v[2:3], v[2:3], v[24:25]
	v_pk_mul_f32 v[6:7], v[6:7], v[24:25]
	v_pk_mul_f32 v[0:1], v[0:1], v[26:27]
	v_mov_b32_e32 v19, v10
	v_mov_b32_e32 v29, v11
	v_pk_fma_f32 v[24:25], v[12:13], v[26:27], v[40:41] neg_lo:[0,0,1] neg_hi:[0,0,1]
	v_mov_b32_e32 v33, v15
	v_mov_b32_e32 v31, v14
	v_pk_fma_f32 v[8:9], v[12:13], v[20:21], v[8:9]
	v_mov_b32_e32 v35, v2
	v_mov_b32_e32 v37, v3
	v_pk_fma_f32 v[12:13], v[4:5], v[26:27], v[42:43] neg_lo:[0,0,1] neg_hi:[0,0,1]
	v_mov_b32_e32 v39, v7
	v_mov_b32_e32 v23, v6
	v_pk_fma_f32 v[0:1], v[4:5], v[20:21], v[0:1]
	v_pk_add_f32 v[14:15], v[18:19], v[28:29] neg_lo:[0,1] neg_hi:[0,1]
	v_pk_add_f32 v[10:11], v[32:33], v[30:31]
	v_pk_add_f32 v[6:7], v[34:35], v[36:37] neg_lo:[0,1] neg_hi:[0,1]
	v_pk_add_f32 v[2:3], v[38:39], v[22:23]
	v_mov_b32_e32 v4, v12
	v_mov_b32_e32 v5, v13
	v_mov_b32_e32 v12, v24
	v_mov_b32_e32 v13, v25
	s_branch .LBB0_743
